# S5 pass2 recurrence step as four scalar FMAs (same association as the packed form) with interleaved state rows
# speedup vs baseline: 1.0052x; 1.0052x over previous
.LBB0_1787:
	s_or_b64 exec, exec, s[0:1]
	s_movk_i32 s1, 0x3200
	v_mul_lo_u32 v72, v82, s1
	v_add_u32_e32 v81, 0, v72
	s_waitcnt vmcnt(0) lgkmcnt(0)
	v_mov_b32_e32 v158, 0x5040100
	v_mov_b32_e32 v159, 0x7060302
	v_perm_b32 v24, v142, v140, v158
	v_perm_b32 v25, v142, v140, v159
	v_perm_b32 v26, v143, v141, v158
	v_perm_b32 v27, v143, v141, v159
	v_perm_b32 v20, v146, v144, v158
	v_perm_b32 v21, v146, v144, v159
	v_perm_b32 v22, v147, v145, v158
	v_perm_b32 v23, v147, v145, v159
	v_perm_b32 v16, v150, v148, v158
	v_perm_b32 v17, v150, v148, v159
	v_perm_b32 v18, v151, v149, v158
	v_perm_b32 v19, v151, v149, v159
	v_perm_b32 v12, v154, v152, v158
	v_perm_b32 v13, v154, v152, v159
	v_perm_b32 v14, v155, v153, v158
	v_perm_b32 v15, v155, v153, v159
	v_mfma_f32_16x16x32_bf16 v[84:87], v[0:3], v[32:35], 0
	v_mul_u32_u24_e32 v72, 0x210, v83
	v_lshlrev_b32_e32 v73, 2, v79
	v_lshlrev_b32_e32 v72, 2, v72
	v_mfma_f32_16x16x32_bf16 v[96:99], v[0:3], v[28:31], 0
	v_add3_u32 v73, v81, v73, v72
	v_add_u32_e32 v74, 0x400, v73
	s_nop 5
	ds_write2_b32 v73, v84, v96 offset1:16
	ds_write2_b32 v73, v85, v97 offset0:132 offset1:148
	ds_write2_b32 v74, v86, v98 offset0:8 offset1:24
	ds_write2_b32 v74, v87, v99 offset0:140 offset1:156
	v_mfma_f32_16x16x32_bf16 v[82:85], v[0:3], v[40:43], 0
	v_lshl_add_u32 v75, v78, 2, v81
	s_cmp_gt_i32 s9, 3
	s_cselect_b32 s0, 0x87, 3
	v_mfma_f32_16x16x32_bf16 v[86:89], v[0:3], v[36:39], 0
	s_nop 7
	ds_write2_b32 v73, v82, v86 offset0:32 offset1:48
	ds_write2_b32 v73, v83, v87 offset0:164 offset1:180
	ds_write2_b32 v74, v84, v88 offset0:40 offset1:56
	ds_write2_b32 v74, v85, v89 offset0:172 offset1:188
	v_mfma_f32_16x16x32_bf16 v[82:85], v[0:3], v[48:51], 0
	s_sub_i32 s0, s0, s9
	v_mul_u32_u24_e32 v94, 0x110, v79
	v_add_u32_e32 v79, 64, v75
	v_mfma_f32_16x16x32_bf16 v[86:89], v[0:3], v[44:47], 0
	s_nop 7
	ds_write2_b32 v73, v82, v86 offset0:64 offset1:80
	ds_write2_b32 v73, v83, v87 offset0:196 offset1:212
	ds_write2_b32 v74, v84, v88 offset0:72 offset1:88
	ds_write2_b32 v74, v85, v89 offset0:204 offset1:220
	v_mfma_f32_16x16x32_bf16 v[82:85], v[0:3], v[56:59], 0
	v_add_u32_e32 v86, 0x90, v75
	v_add_u32_e32 v87, 0xa0, v75
	v_add_u32_e32 v88, 0xb0, v75
	v_mfma_f32_16x16x32_bf16 v[0:3], v[0:3], v[52:55], 0
	s_nop 7
	ds_write2_b32 v73, v82, v0 offset0:96 offset1:112
	ds_write2_b32 v73, v83, v1 offset0:228 offset1:244
	ds_write2_b32 v74, v84, v2 offset0:104 offset1:120
	ds_write2_b32 v74, v85, v3 offset0:236 offset1:252
	v_lshlrev_b32_e32 v0, 1, v78
	s_waitcnt vmcnt(0) lgkmcnt(0)
	v_sub_u32_e32 v72, v75, v0
	ds_read2st64_b32 v[0:1], v75 offset1:1
	ds_read2_b32 v[140:141], v75 offset0:132 offset1:196
	v_add_u32_e32 v142, 32, v75
	ds_read2st64_b32 v[144:145], v142 offset0:4 offset1:5
	v_add_u32_e32 v143, 48, v75
	ds_read2st64_b32 v[146:147], v143 offset0:6 offset1:7
	ds_read2st64_b32 v[148:149], v79 offset0:8 offset1:9
	v_add_u32_e32 v150, 0x50, v75
	ds_read2st64_b32 v[152:153], v150 offset0:10 offset1:11
	v_add_u32_e32 v151, 0x60, v75
	ds_read2st64_b32 v[154:155], v151 offset0:12 offset1:13
	v_add_u32_e32 v156, 0x70, v75
	ds_read2st64_b32 v[158:159], v156 offset0:14 offset1:15
	v_add_u32_e32 v157, 0x80, v75
	ds_read2st64_b32 v[160:161], v157 offset0:16 offset1:17
	ds_read2st64_b32 v[162:163], v86 offset0:18 offset1:19
	ds_read2st64_b32 v[164:165], v87 offset0:20 offset1:21
	ds_read2st64_b32 v[166:167], v88 offset0:22 offset1:23
	v_add_u32_e32 v168, 0xc0, v75
	ds_read2st64_b32 v[170:171], v168 offset0:24 offset1:25
	v_add_u32_e32 v169, 0xd0, v75
	ds_read2st64_b32 v[172:173], v169 offset0:26 offset1:27
	v_add_u32_e32 v174, 0xe0, v75
	ds_read2st64_b32 v[176:177], v174 offset0:28 offset1:29
	v_add_u32_e32 v175, 0xf0, v75
	ds_read2st64_b32 v[178:179], v175 offset0:30 offset1:31
	v_mov_b32_e32 v186, v70
	v_mov_b32_e32 v187, v71
	v_add_u32_e32 v78, 48, v75
	v_add_u32_e32 v82, 0x50, v75
	s_waitcnt lgkmcnt(0)
	v_fma_f32 v184, -v67, v187, v0
	v_fma_f32 v185, v67, v186, v1
	v_fma_f32 v188, v66, v186, v184
	v_fma_f32 v189, v66, v187, v185
	v_cvt_pk_bf16_f32 v190, v188, v189
	v_and_b32_e32 v191, 63, v207
	v_lshl_add_u32 v191, v191, 1, v72
	ds_write_b32 v191, v190 offset:8448
	v_add_u32_e32 v71, 32, v75
	v_add_u32_e32 v83, 0x60, v75
	v_fma_f32 v184, -v67, v189, v140
	v_fma_f32 v185, v67, v188, v141
	v_fma_f32 v186, v66, v188, v184
	v_fma_f32 v187, v66, v189, v185
	v_cvt_pk_bf16_f32 v190, v186, v187
	ds_write_b32 v191, v190 offset:8720
	v_add_u32_e32 v84, 0x70, v75
	v_add_u32_e32 v85, 0x80, v75
	v_fma_f32 v184, -v67, v187, v144
	v_fma_f32 v185, v67, v186, v145
	v_fma_f32 v188, v66, v186, v184
	v_fma_f32 v189, v66, v187, v185
	v_cvt_pk_bf16_f32 v190, v188, v189
	ds_write_b32 v191, v190 offset:8992
	v_add_u32_e32 v89, 0xc0, v75
	v_add_u32_e32 v91, 0xd0, v75
	v_fma_f32 v184, -v67, v189, v146
	v_fma_f32 v185, v67, v188, v147
	v_fma_f32 v186, v66, v188, v184
	v_fma_f32 v187, v66, v189, v185
	v_cvt_pk_bf16_f32 v190, v186, v187
	ds_write_b32 v191, v190 offset:9264
	v_add_u32_e32 v92, 0xe0, v75
	v_add_u32_e32 v93, 0xf0, v75
	v_fma_f32 v184, -v67, v187, v148
	v_fma_f32 v185, v67, v186, v149
	v_fma_f32 v188, v66, v186, v184
	v_fma_f32 v189, v66, v187, v185
	v_cvt_pk_bf16_f32 v190, v188, v189
	ds_write_b32 v191, v190 offset:9536
	v_mfma_f32_16x16x32_bf16 v[98:101], v[4:7], v[28:31], 0
	s_or_b32 s1, s2, 0x84
	v_fma_f32 v184, -v67, v189, v152
	v_fma_f32 v185, v67, v188, v153
	v_fma_f32 v186, v66, v188, v184
	v_fma_f32 v187, v66, v189, v185
	v_cvt_pk_bf16_f32 v190, v186, v187
	ds_write_b32 v191, v190 offset:9808
	s_ashr_i32 s2, s0, 31
	v_fma_f32 v184, -v67, v187, v154
	v_fma_f32 v185, v67, v186, v155
	v_fma_f32 v188, v66, v186, v184
	v_fma_f32 v189, v66, v187, v185
	v_cvt_pk_bf16_f32 v190, v188, v189
	ds_write_b32 v191, v190 offset:10080
	v_fma_f32 v184, -v67, v189, v158
	v_fma_f32 v185, v67, v188, v159
	v_fma_f32 v186, v66, v188, v184
	v_fma_f32 v187, v66, v189, v185
	v_cvt_pk_bf16_f32 v190, v186, v187
	ds_write_b32 v191, v190 offset:10352
	v_fma_f32 v184, -v67, v187, v160
	v_fma_f32 v185, v67, v186, v161
	v_fma_f32 v188, v66, v186, v184
	v_fma_f32 v189, v66, v187, v185
	v_cvt_pk_bf16_f32 v190, v188, v189
	ds_write_b32 v191, v190 offset:10624
	v_fma_f32 v184, -v67, v189, v162
	v_fma_f32 v185, v67, v188, v163
	v_fma_f32 v186, v66, v188, v184
	v_fma_f32 v187, v66, v189, v185
	v_cvt_pk_bf16_f32 v190, v186, v187
	ds_write_b32 v191, v190 offset:10896
	v_fma_f32 v184, -v67, v187, v164
	v_fma_f32 v185, v67, v186, v165
	v_fma_f32 v188, v66, v186, v184
	v_fma_f32 v189, v66, v187, v185
	v_cvt_pk_bf16_f32 v190, v188, v189
	ds_write_b32 v191, v190 offset:11168
	v_fma_f32 v184, -v67, v189, v166
	v_fma_f32 v185, v67, v188, v167
	v_fma_f32 v186, v66, v188, v184
	v_fma_f32 v187, v66, v189, v185
	v_cvt_pk_bf16_f32 v190, v186, v187
	ds_write_b32 v191, v190 offset:11440
	v_fma_f32 v184, -v67, v187, v170
	v_fma_f32 v185, v67, v186, v171
	v_fma_f32 v188, v66, v186, v184
	v_fma_f32 v189, v66, v187, v185
	v_cvt_pk_bf16_f32 v190, v188, v189
	ds_write_b32 v191, v190 offset:11712
	v_fma_f32 v184, -v67, v189, v172
	v_fma_f32 v185, v67, v188, v173
	v_fma_f32 v186, v66, v188, v184
	v_fma_f32 v187, v66, v189, v185
	v_cvt_pk_bf16_f32 v190, v186, v187
	ds_write_b32 v191, v190 offset:11984
	v_fma_f32 v184, -v67, v187, v176
	v_fma_f32 v185, v67, v186, v177
	v_fma_f32 v188, v66, v186, v184
	v_fma_f32 v189, v66, v187, v185
	v_cvt_pk_bf16_f32 v190, v188, v189
	ds_write_b32 v191, v190 offset:12256
	v_fma_f32 v184, -v67, v189, v178
	v_fma_f32 v185, v67, v188, v179
	v_fma_f32 v186, v66, v188, v184
	v_fma_f32 v187, v66, v189, v185
	v_mov_b32_e32 v102, v186
	v_mov_b32_e32 v103, v187
	v_cvt_pk_bf16_f32 v190, v186, v187
	ds_write_b32 v191, v190 offset:12528
	v_add3_u32 v70, v81, v128, v94
	s_waitcnt vmcnt(0) lgkmcnt(0)
	ds_read_b128 v[0:3], v70 offset:8448
	ds_read_b128 v[94:97], v70 offset:8512
	s_waitcnt lgkmcnt(1)
	v_mfma_f32_16x16x32_bf16 v[0:3], v[0:3], v[24:27], 0
	s_waitcnt lgkmcnt(0)
	v_mfma_f32_16x16x32_bf16 v[0:3], v[94:97], v[20:23], v[0:3]
	ds_read_b128 v[94:97], v70 offset:8576
	s_waitcnt lgkmcnt(0)
	v_mfma_f32_16x16x32_bf16 v[0:3], v[94:97], v[16:19], v[0:3]
	ds_read_b128 v[94:97], v70 offset:8640
	s_waitcnt lgkmcnt(0)
	v_mfma_f32_16x16x32_bf16 v[0:3], v[94:97], v[12:15], v[0:3]
	v_mfma_f32_16x16x32_bf16 v[94:97], v[4:7], v[32:35], 0
	s_nop 7
	ds_write2_b32 v73, v94, v98 offset1:16
	ds_write2_b32 v73, v95, v99 offset0:132 offset1:148
	ds_write2_b32 v74, v96, v100 offset0:8 offset1:24
	ds_write2_b32 v74, v97, v101 offset0:140 offset1:156
	v_mfma_f32_16x16x32_bf16 v[94:97], v[4:7], v[40:43], 0
	v_mfma_f32_16x16x32_bf16 v[98:101], v[4:7], v[36:39], 0
	s_nop 7
	ds_write2_b32 v73, v94, v98 offset0:32 offset1:48
	ds_write2_b32 v73, v95, v99 offset0:164 offset1:180
	ds_write2_b32 v74, v96, v100 offset0:40 offset1:56
	ds_write2_b32 v74, v97, v101 offset0:172 offset1:188
	v_mfma_f32_16x16x32_bf16 v[94:97], v[4:7], v[48:51], 0
	v_mfma_f32_16x16x32_bf16 v[98:101], v[4:7], v[44:47], 0
	s_nop 7
	ds_write2_b32 v73, v94, v98 offset0:64 offset1:80
	ds_write2_b32 v73, v95, v99 offset0:196 offset1:212
	ds_write2_b32 v74, v96, v100 offset0:72 offset1:88
	ds_write2_b32 v74, v97, v101 offset0:204 offset1:220
	v_mfma_f32_16x16x32_bf16 v[94:97], v[4:7], v[56:59], 0
	v_mfma_f32_16x16x32_bf16 v[4:7], v[4:7], v[52:55], 0
	s_nop 7
	ds_write2_b32 v73, v94, v4 offset0:96 offset1:112
	ds_write2_b32 v73, v95, v5 offset0:228 offset1:244
	ds_write2_b32 v74, v96, v6 offset0:104 offset1:120
	ds_write2_b32 v74, v97, v7 offset0:236 offset1:252
	s_waitcnt vmcnt(0) lgkmcnt(0)
	ds_read2st64_b32 v[4:5], v75 offset1:1
	ds_read2_b32 v[140:141], v75 offset0:132 offset1:196
	ds_read2st64_b32 v[142:143], v71 offset0:4 offset1:5
	ds_read2st64_b32 v[144:145], v78 offset0:6 offset1:7
	ds_read2st64_b32 v[146:147], v79 offset0:8 offset1:9
	ds_read2st64_b32 v[148:149], v82 offset0:10 offset1:11
	ds_read2st64_b32 v[150:151], v83 offset0:12 offset1:13
	ds_read2st64_b32 v[152:153], v84 offset0:14 offset1:15
	ds_read2st64_b32 v[154:155], v85 offset0:16 offset1:17
	ds_read2st64_b32 v[156:157], v86 offset0:18 offset1:19
	ds_read2st64_b32 v[158:159], v87 offset0:20 offset1:21
	ds_read2st64_b32 v[160:161], v88 offset0:22 offset1:23
	ds_read2st64_b32 v[162:163], v89 offset0:24 offset1:25
	ds_read2st64_b32 v[164:165], v91 offset0:26 offset1:27
	ds_read2st64_b32 v[166:167], v92 offset0:28 offset1:29
	ds_read2st64_b32 v[168:169], v93 offset0:30 offset1:31
	v_mov_b32_e32 v186, v102
	v_mov_b32_e32 v187, v103
	v_mfma_f32_16x16x32_bf16 v[98:101], v[8:11], v[28:31], 0
	s_waitcnt lgkmcnt(0)
	v_fma_f32 v184, -v67, v187, v4
	v_fma_f32 v185, v67, v186, v5
	v_fma_f32 v188, v66, v186, v184
	v_fma_f32 v189, v66, v187, v185
	v_cvt_pk_bf16_f32 v190, v188, v189
	v_and_b32_e32 v191, 63, v207
	v_lshl_add_u32 v191, v191, 1, v72
	ds_write_b32 v191, v190 offset:8448
	v_mfma_f32_16x16x32_bf16 v[28:31], v[60:63], v[28:31], 0
	v_fma_f32 v184, -v67, v189, v140
	v_fma_f32 v185, v67, v188, v141
	v_fma_f32 v186, v66, v188, v184
	v_fma_f32 v187, v66, v189, v185
	v_cvt_pk_bf16_f32 v190, v186, v187
	ds_write_b32 v191, v190 offset:8720
	v_fma_f32 v184, -v67, v187, v142
	v_fma_f32 v185, v67, v186, v143
	v_fma_f32 v188, v66, v186, v184
	v_fma_f32 v189, v66, v187, v185
	v_cvt_pk_bf16_f32 v190, v188, v189
	ds_write_b32 v191, v190 offset:8992
	v_fma_f32 v184, -v67, v189, v144
	v_fma_f32 v185, v67, v188, v145
	v_fma_f32 v186, v66, v188, v184
	v_fma_f32 v187, v66, v189, v185
	v_cvt_pk_bf16_f32 v190, v186, v187
	ds_write_b32 v191, v190 offset:9264
	v_fma_f32 v184, -v67, v187, v146
	v_fma_f32 v185, v67, v186, v147
	v_fma_f32 v188, v66, v186, v184
	v_fma_f32 v189, v66, v187, v185
	v_cvt_pk_bf16_f32 v190, v188, v189
	ds_write_b32 v191, v190 offset:9536
	v_fma_f32 v184, -v67, v189, v148
	v_fma_f32 v185, v67, v188, v149
	v_fma_f32 v186, v66, v188, v184
	v_fma_f32 v187, v66, v189, v185
	v_cvt_pk_bf16_f32 v190, v186, v187
	ds_write_b32 v191, v190 offset:9808
	v_fma_f32 v184, -v67, v187, v150
	v_fma_f32 v185, v67, v186, v151
	v_fma_f32 v188, v66, v186, v184
	v_fma_f32 v189, v66, v187, v185
	v_cvt_pk_bf16_f32 v190, v188, v189
	ds_write_b32 v191, v190 offset:10080
	v_fma_f32 v184, -v67, v189, v152
	v_fma_f32 v185, v67, v188, v153
	v_fma_f32 v186, v66, v188, v184
	v_fma_f32 v187, v66, v189, v185
	v_cvt_pk_bf16_f32 v190, v186, v187
	ds_write_b32 v191, v190 offset:10352
	v_fma_f32 v184, -v67, v187, v154
	v_fma_f32 v185, v67, v186, v155
	v_fma_f32 v188, v66, v186, v184
	v_fma_f32 v189, v66, v187, v185
	v_cvt_pk_bf16_f32 v190, v188, v189
	ds_write_b32 v191, v190 offset:10624
	v_fma_f32 v184, -v67, v189, v156
	v_fma_f32 v185, v67, v188, v157
	v_fma_f32 v186, v66, v188, v184
	v_fma_f32 v187, v66, v189, v185
	v_cvt_pk_bf16_f32 v190, v186, v187
	ds_write_b32 v191, v190 offset:10896
	v_fma_f32 v184, -v67, v187, v158
	v_fma_f32 v185, v67, v186, v159
	v_fma_f32 v188, v66, v186, v184
	v_fma_f32 v189, v66, v187, v185
	v_cvt_pk_bf16_f32 v190, v188, v189
	ds_write_b32 v191, v190 offset:11168
	v_fma_f32 v184, -v67, v189, v160
	v_fma_f32 v185, v67, v188, v161
	v_fma_f32 v186, v66, v188, v184
	v_fma_f32 v187, v66, v189, v185
	v_cvt_pk_bf16_f32 v190, v186, v187
	ds_write_b32 v191, v190 offset:11440
	v_fma_f32 v184, -v67, v187, v162
	v_fma_f32 v185, v67, v186, v163
	v_fma_f32 v188, v66, v186, v184
	v_fma_f32 v189, v66, v187, v185
	v_cvt_pk_bf16_f32 v190, v188, v189
	ds_write_b32 v191, v190 offset:11712
	v_fma_f32 v184, -v67, v189, v164
	v_fma_f32 v185, v67, v188, v165
	v_fma_f32 v186, v66, v188, v184
	v_fma_f32 v187, v66, v189, v185
	v_cvt_pk_bf16_f32 v190, v186, v187
	ds_write_b32 v191, v190 offset:11984
	v_fma_f32 v184, -v67, v187, v166
	v_fma_f32 v185, v67, v186, v167
	v_fma_f32 v188, v66, v186, v184
	v_fma_f32 v189, v66, v187, v185
	v_cvt_pk_bf16_f32 v190, v188, v189
	ds_write_b32 v191, v190 offset:12256
	v_fma_f32 v184, -v67, v189, v168
	v_fma_f32 v185, v67, v188, v169
	v_fma_f32 v186, v66, v188, v184
	v_fma_f32 v187, v66, v189, v185
	v_mov_b32_e32 v102, v186
	v_mov_b32_e32 v103, v187
	v_cvt_pk_bf16_f32 v190, v186, v187
	ds_write_b32 v191, v190 offset:12528
	s_waitcnt vmcnt(0) lgkmcnt(0)
	ds_read_b128 v[4:7], v70 offset:8448
	ds_read_b128 v[94:97], v70 offset:8512
	s_waitcnt lgkmcnt(1)
	v_mfma_f32_16x16x32_bf16 v[4:7], v[4:7], v[24:27], 0
	s_waitcnt lgkmcnt(0)
	v_mfma_f32_16x16x32_bf16 v[4:7], v[94:97], v[20:23], v[4:7]
	ds_read_b128 v[94:97], v70 offset:8576
	s_waitcnt lgkmcnt(0)
	v_mfma_f32_16x16x32_bf16 v[4:7], v[94:97], v[16:19], v[4:7]
	ds_read_b128 v[94:97], v70 offset:8640
	s_waitcnt lgkmcnt(0)
	v_mfma_f32_16x16x32_bf16 v[4:7], v[94:97], v[12:15], v[4:7]
	v_mfma_f32_16x16x32_bf16 v[94:97], v[8:11], v[32:35], 0
	s_nop 7
	ds_write2_b32 v73, v94, v98 offset1:16
	ds_write2_b32 v73, v95, v99 offset0:132 offset1:148
	ds_write2_b32 v74, v96, v100 offset0:8 offset1:24
	ds_write2_b32 v74, v97, v101 offset0:140 offset1:156
	v_mfma_f32_16x16x32_bf16 v[94:97], v[8:11], v[40:43], 0
	v_mfma_f32_16x16x32_bf16 v[98:101], v[8:11], v[36:39], 0
	s_nop 7
	ds_write2_b32 v73, v94, v98 offset0:32 offset1:48
	ds_write2_b32 v73, v95, v99 offset0:164 offset1:180
	ds_write2_b32 v74, v96, v100 offset0:40 offset1:56
	ds_write2_b32 v74, v97, v101 offset0:172 offset1:188
	v_mfma_f32_16x16x32_bf16 v[94:97], v[8:11], v[48:51], 0
	v_mfma_f32_16x16x32_bf16 v[98:101], v[8:11], v[44:47], 0
	s_nop 7
	ds_write2_b32 v73, v94, v98 offset0:64 offset1:80
	ds_write2_b32 v73, v95, v99 offset0:196 offset1:212
	ds_write2_b32 v74, v96, v100 offset0:72 offset1:88
	ds_write2_b32 v74, v97, v101 offset0:204 offset1:220
	v_mfma_f32_16x16x32_bf16 v[94:97], v[8:11], v[56:59], 0
	v_mfma_f32_16x16x32_bf16 v[8:11], v[8:11], v[52:55], 0
	s_nop 7
	ds_write2_b32 v73, v94, v8 offset0:96 offset1:112
	ds_write2_b32 v73, v95, v9 offset0:228 offset1:244
	ds_write2_b32 v74, v96, v10 offset0:104 offset1:120
	ds_write2_b32 v74, v97, v11 offset0:236 offset1:252
	s_waitcnt vmcnt(0) lgkmcnt(0)
	ds_read2st64_b32 v[8:9], v75 offset1:1
	ds_read2_b32 v[140:141], v75 offset0:132 offset1:196
	ds_read2st64_b32 v[142:143], v71 offset0:4 offset1:5
	ds_read2st64_b32 v[144:145], v78 offset0:6 offset1:7
	ds_read2st64_b32 v[146:147], v79 offset0:8 offset1:9
	ds_read2st64_b32 v[148:149], v82 offset0:10 offset1:11
	ds_read2st64_b32 v[150:151], v83 offset0:12 offset1:13
	ds_read2st64_b32 v[152:153], v84 offset0:14 offset1:15
	ds_read2st64_b32 v[154:155], v85 offset0:16 offset1:17
	ds_read2st64_b32 v[156:157], v86 offset0:18 offset1:19
	ds_read2st64_b32 v[158:159], v87 offset0:20 offset1:21
	ds_read2st64_b32 v[160:161], v88 offset0:22 offset1:23
	ds_read2st64_b32 v[162:163], v89 offset0:24 offset1:25
	ds_read2st64_b32 v[164:165], v91 offset0:26 offset1:27
	ds_read2st64_b32 v[166:167], v92 offset0:28 offset1:29
	ds_read2st64_b32 v[168:169], v93 offset0:30 offset1:31
	v_mov_b32_e32 v186, v102
	v_mov_b32_e32 v187, v103
	v_mfma_f32_16x16x32_bf16 v[32:35], v[60:63], v[32:35], 0
	s_waitcnt lgkmcnt(0)
	v_fma_f32 v184, -v67, v187, v8
	v_fma_f32 v185, v67, v186, v9
	v_fma_f32 v188, v66, v186, v184
	v_fma_f32 v189, v66, v187, v185
	v_cvt_pk_bf16_f32 v190, v188, v189
	v_and_b32_e32 v191, 63, v207
	v_lshl_add_u32 v191, v191, 1, v72
	ds_write_b32 v191, v190 offset:8448
	v_fma_f32 v184, -v67, v189, v140
	v_fma_f32 v185, v67, v188, v141
	v_fma_f32 v186, v66, v188, v184
	v_fma_f32 v187, v66, v189, v185
	v_cvt_pk_bf16_f32 v190, v186, v187
	ds_write_b32 v191, v190 offset:8720
	v_fma_f32 v184, -v67, v187, v142
	v_fma_f32 v185, v67, v186, v143
	v_fma_f32 v188, v66, v186, v184
	v_fma_f32 v189, v66, v187, v185
	v_cvt_pk_bf16_f32 v190, v188, v189
	ds_write_b32 v191, v190 offset:8992
	v_fma_f32 v184, -v67, v189, v144
	v_fma_f32 v185, v67, v188, v145
	v_fma_f32 v186, v66, v188, v184
	v_fma_f32 v187, v66, v189, v185
	v_cvt_pk_bf16_f32 v190, v186, v187
	ds_write_b32 v191, v190 offset:9264
	v_fma_f32 v184, -v67, v187, v146
	v_fma_f32 v185, v67, v186, v147
	v_fma_f32 v188, v66, v186, v184
	v_fma_f32 v189, v66, v187, v185
	v_cvt_pk_bf16_f32 v190, v188, v189
	ds_write_b32 v191, v190 offset:9536
	v_fma_f32 v184, -v67, v189, v148
	v_fma_f32 v185, v67, v188, v149
	v_fma_f32 v186, v66, v188, v184
	v_fma_f32 v187, v66, v189, v185
	v_cvt_pk_bf16_f32 v190, v186, v187
	ds_write_b32 v191, v190 offset:9808
	v_fma_f32 v184, -v67, v187, v150
	v_fma_f32 v185, v67, v186, v151
	v_fma_f32 v188, v66, v186, v184
	v_fma_f32 v189, v66, v187, v185
	v_cvt_pk_bf16_f32 v190, v188, v189
	ds_write_b32 v191, v190 offset:10080
	v_fma_f32 v184, -v67, v189, v152
	v_fma_f32 v185, v67, v188, v153
	v_fma_f32 v186, v66, v188, v184
	v_fma_f32 v187, v66, v189, v185
	v_cvt_pk_bf16_f32 v190, v186, v187
	ds_write_b32 v191, v190 offset:10352
	v_fma_f32 v184, -v67, v187, v154
	v_fma_f32 v185, v67, v186, v155
	v_fma_f32 v188, v66, v186, v184
	v_fma_f32 v189, v66, v187, v185
	v_cvt_pk_bf16_f32 v190, v188, v189
	ds_write_b32 v191, v190 offset:10624
	v_fma_f32 v184, -v67, v189, v156
	v_fma_f32 v185, v67, v188, v157
	v_fma_f32 v186, v66, v188, v184
	v_fma_f32 v187, v66, v189, v185
	v_cvt_pk_bf16_f32 v190, v186, v187
	ds_write_b32 v191, v190 offset:10896
	v_fma_f32 v184, -v67, v187, v158
	v_fma_f32 v185, v67, v186, v159
	v_fma_f32 v188, v66, v186, v184
	v_fma_f32 v189, v66, v187, v185
	v_cvt_pk_bf16_f32 v190, v188, v189
	ds_write_b32 v191, v190 offset:11168
	v_fma_f32 v184, -v67, v189, v160
	v_fma_f32 v185, v67, v188, v161
	v_fma_f32 v186, v66, v188, v184
	v_fma_f32 v187, v66, v189, v185
	v_cvt_pk_bf16_f32 v190, v186, v187
	ds_write_b32 v191, v190 offset:11440
	v_fma_f32 v184, -v67, v187, v162
	v_fma_f32 v185, v67, v186, v163
	v_fma_f32 v188, v66, v186, v184
	v_fma_f32 v189, v66, v187, v185
	v_cvt_pk_bf16_f32 v190, v188, v189
	ds_write_b32 v191, v190 offset:11712
	v_fma_f32 v184, -v67, v189, v164
	v_fma_f32 v185, v67, v188, v165
	v_fma_f32 v186, v66, v188, v184
	v_fma_f32 v187, v66, v189, v185
	v_cvt_pk_bf16_f32 v190, v186, v187
	ds_write_b32 v191, v190 offset:11984
	v_fma_f32 v184, -v67, v187, v166
	v_fma_f32 v185, v67, v186, v167
	v_fma_f32 v188, v66, v186, v184
	v_fma_f32 v189, v66, v187, v185
	v_cvt_pk_bf16_f32 v190, v188, v189
	ds_write_b32 v191, v190 offset:12256
	v_fma_f32 v184, -v67, v189, v168
	v_fma_f32 v185, v67, v188, v169
	v_fma_f32 v186, v66, v188, v184
	v_fma_f32 v187, v66, v189, v185
	v_mov_b32_e32 v98, v186
	v_mov_b32_e32 v99, v187
	v_cvt_pk_bf16_f32 v190, v186, v187
	ds_write_b32 v191, v190 offset:12528
	s_waitcnt vmcnt(0) lgkmcnt(0)
	ds_read_b128 v[8:11], v70 offset:8448
	ds_read_b128 v[94:97], v70 offset:8512
	s_waitcnt lgkmcnt(1)
	v_mfma_f32_16x16x32_bf16 v[8:11], v[8:11], v[24:27], 0
	s_waitcnt lgkmcnt(0)
	v_mfma_f32_16x16x32_bf16 v[8:11], v[94:97], v[20:23], v[8:11]
	ds_read_b128 v[94:97], v70 offset:8576
	s_waitcnt lgkmcnt(0)
	v_mfma_f32_16x16x32_bf16 v[8:11], v[94:97], v[16:19], v[8:11]
	ds_read_b128 v[94:97], v70 offset:8640
	ds_write2_b32 v73, v32, v28 offset1:16
	ds_write2_b32 v73, v33, v29 offset0:132 offset1:148
	ds_write2_b32 v74, v34, v30 offset0:8 offset1:24
	ds_write2_b32 v74, v35, v31 offset0:140 offset1:156
	v_mfma_f32_16x16x32_bf16 v[28:31], v[60:63], v[40:43], 0
	v_mov_b32_e32 v40, 0
	v_mov_b32_e32 v41, 0
	v_mov_b32_e32 v42, 0
	v_mfma_f32_16x16x32_bf16 v[32:35], v[60:63], v[36:39], 0
	s_nop 7
	ds_write2_b32 v73, v28, v32 offset0:32 offset1:48
	ds_write2_b32 v73, v29, v33 offset0:164 offset1:180
	ds_write2_b32 v74, v30, v34 offset0:40 offset1:56
	ds_write2_b32 v74, v31, v35 offset0:172 offset1:188
	v_mfma_f32_16x16x32_bf16 v[28:31], v[60:63], v[48:51], 0
	v_mov_b32_e32 v36, 0
	v_mov_b32_e32 v43, 0
	v_mfma_f32_16x16x32_bf16 v[32:35], v[60:63], v[44:47], 0
	s_nop 7
	ds_write2_b32 v73, v28, v32 offset0:64 offset1:80
	ds_write2_b32 v73, v29, v33 offset0:196 offset1:212
	ds_write2_b32 v74, v30, v34 offset0:72 offset1:88
	ds_write2_b32 v74, v31, v35 offset0:204 offset1:220
	v_mfma_f32_16x16x32_bf16 v[28:31], v[60:63], v[56:59], 0
	v_mfma_f32_16x16x32_bf16 v[32:35], v[60:63], v[52:55], 0
	s_nop 7
	ds_write2_b32 v73, v28, v32 offset0:96 offset1:112
	ds_write2_b32 v73, v29, v33 offset0:228 offset1:244
	ds_write2_b32 v74, v30, v34 offset0:104 offset1:120
	ds_write2_b32 v74, v31, v35 offset0:236 offset1:252
	s_waitcnt vmcnt(0) lgkmcnt(0)
	ds_read2st64_b32 v[28:29], v75 offset1:1
	ds_read2_b32 v[140:141], v75 offset0:132 offset1:196
	ds_read2st64_b32 v[142:143], v71 offset0:4 offset1:5
	ds_read2st64_b32 v[144:145], v78 offset0:6 offset1:7
	ds_read2st64_b32 v[146:147], v79 offset0:8 offset1:9
	ds_read2st64_b32 v[148:149], v82 offset0:10 offset1:11
	ds_read2st64_b32 v[150:151], v83 offset0:12 offset1:13
	ds_read2st64_b32 v[152:153], v84 offset0:14 offset1:15
	ds_read2st64_b32 v[154:155], v85 offset0:16 offset1:17
	ds_read2st64_b32 v[156:157], v86 offset0:18 offset1:19
	ds_read2st64_b32 v[158:159], v87 offset0:20 offset1:21
	ds_read2st64_b32 v[160:161], v88 offset0:22 offset1:23
	ds_read2st64_b32 v[162:163], v89 offset0:24 offset1:25
	ds_read2st64_b32 v[164:165], v91 offset0:26 offset1:27
	ds_read2st64_b32 v[166:167], v92 offset0:28 offset1:29
	ds_read2st64_b32 v[168:169], v93 offset0:30 offset1:31
	v_mov_b32_e32 v186, v98
	v_mov_b32_e32 v187, v99
	s_waitcnt lgkmcnt(0)
	v_mfma_f32_16x16x32_bf16 v[8:11], v[94:97], v[12:15], v[8:11]
	v_fma_f32 v184, -v67, v187, v28
	v_fma_f32 v185, v67, v186, v29
	v_fma_f32 v188, v66, v186, v184
	v_fma_f32 v189, v66, v187, v185
	v_cvt_pk_bf16_f32 v190, v188, v189
	v_and_b32_e32 v191, 63, v207
	v_lshl_add_u32 v191, v191, 1, v72
	ds_write_b32 v191, v190 offset:8448
	v_fma_f32 v184, -v67, v189, v140
	v_fma_f32 v185, v67, v188, v141
	v_fma_f32 v186, v66, v188, v184
	v_fma_f32 v187, v66, v189, v185
	v_cvt_pk_bf16_f32 v190, v186, v187
	ds_write_b32 v191, v190 offset:8720
	v_fma_f32 v184, -v67, v187, v142
	v_fma_f32 v185, v67, v186, v143
	v_fma_f32 v188, v66, v186, v184
	v_fma_f32 v189, v66, v187, v185
	v_cvt_pk_bf16_f32 v190, v188, v189
	ds_write_b32 v191, v190 offset:8992
	v_fma_f32 v184, -v67, v189, v144
	v_fma_f32 v185, v67, v188, v145
	v_fma_f32 v186, v66, v188, v184
	v_fma_f32 v187, v66, v189, v185
	v_cvt_pk_bf16_f32 v190, v186, v187
	ds_write_b32 v191, v190 offset:9264
	v_fma_f32 v184, -v67, v187, v146
	v_fma_f32 v185, v67, v186, v147
	v_fma_f32 v188, v66, v186, v184
	v_fma_f32 v189, v66, v187, v185
	v_cvt_pk_bf16_f32 v190, v188, v189
	ds_write_b32 v191, v190 offset:9536
	v_fma_f32 v184, -v67, v189, v148
	v_fma_f32 v185, v67, v188, v149
	v_fma_f32 v186, v66, v188, v184
	v_fma_f32 v187, v66, v189, v185
	v_cvt_pk_bf16_f32 v190, v186, v187
	ds_write_b32 v191, v190 offset:9808
	v_fma_f32 v184, -v67, v187, v150
	v_fma_f32 v185, v67, v186, v151
	v_fma_f32 v188, v66, v186, v184
	v_fma_f32 v189, v66, v187, v185
	v_cvt_pk_bf16_f32 v190, v188, v189
	ds_write_b32 v191, v190 offset:10080
	v_fma_f32 v184, -v67, v189, v152
	v_fma_f32 v185, v67, v188, v153
	v_fma_f32 v186, v66, v188, v184
	v_fma_f32 v187, v66, v189, v185
	v_cvt_pk_bf16_f32 v190, v186, v187
	ds_write_b32 v191, v190 offset:10352
	v_fma_f32 v184, -v67, v187, v154
	v_fma_f32 v185, v67, v186, v155
	v_fma_f32 v188, v66, v186, v184
	v_fma_f32 v189, v66, v187, v185
	v_cvt_pk_bf16_f32 v190, v188, v189
	ds_write_b32 v191, v190 offset:10624
	v_fma_f32 v184, -v67, v189, v156
	v_fma_f32 v185, v67, v188, v157
	v_fma_f32 v186, v66, v188, v184
	v_fma_f32 v187, v66, v189, v185
	v_cvt_pk_bf16_f32 v190, v186, v187
	ds_write_b32 v191, v190 offset:10896
	v_fma_f32 v184, -v67, v187, v158
	v_fma_f32 v185, v67, v186, v159
	v_fma_f32 v188, v66, v186, v184
	v_fma_f32 v189, v66, v187, v185
	v_cvt_pk_bf16_f32 v190, v188, v189
	ds_write_b32 v191, v190 offset:11168
	v_fma_f32 v184, -v67, v189, v160
	v_fma_f32 v185, v67, v188, v161
	v_fma_f32 v186, v66, v188, v184
	v_fma_f32 v187, v66, v189, v185
	v_cvt_pk_bf16_f32 v190, v186, v187
	ds_write_b32 v191, v190 offset:11440
	v_fma_f32 v184, -v67, v187, v162
	v_fma_f32 v185, v67, v186, v163
	v_fma_f32 v188, v66, v186, v184
	v_fma_f32 v189, v66, v187, v185
	v_cvt_pk_bf16_f32 v190, v188, v189
	ds_write_b32 v191, v190 offset:11712
	v_fma_f32 v184, -v67, v189, v164
	v_fma_f32 v185, v67, v188, v165
	v_fma_f32 v186, v66, v188, v184
	v_fma_f32 v187, v66, v189, v185
	v_cvt_pk_bf16_f32 v190, v186, v187
	ds_write_b32 v191, v190 offset:11984
	v_fma_f32 v184, -v67, v187, v166
	v_fma_f32 v185, v67, v186, v167
	v_fma_f32 v188, v66, v186, v184
	v_fma_f32 v189, v66, v187, v185
	v_cvt_pk_bf16_f32 v190, v188, v189
	ds_write_b32 v191, v190 offset:12256
	v_fma_f32 v184, -v67, v189, v168
	v_fma_f32 v185, v67, v188, v169
	v_fma_f32 v186, v66, v188, v184
	v_fma_f32 v187, v66, v189, v185
	v_mov_b32_e32 v28, v186
	v_mov_b32_e32 v29, v187
	v_cvt_pk_bf16_f32 v190, v186, v187
	ds_write_b32 v191, v190 offset:12528
	s_waitcnt vmcnt(0) lgkmcnt(0)
	ds_read_b128 v[28:31], v70 offset:8448
	s_waitcnt lgkmcnt(0)
	v_mfma_f32_16x16x32_bf16 v[24:27], v[28:31], v[24:27], 0
	ds_read_b128 v[28:31], v70 offset:8512
	s_add_u32 s0, s0, s1
	s_addc_u32 s1, s2, 0
	s_waitcnt lgkmcnt(0)
	v_mfma_f32_16x16x32_bf16 v[20:23], v[28:31], v[20:23], v[24:27]
	s_nop 2
	ds_read_b128 v[24:27], v70 offset:8576
	s_lshl_b64 s[0:1], s[0:1], 14
	s_waitcnt lgkmcnt(0)
	v_mfma_f32_16x16x32_bf16 v[16:19], v[24:27], v[16:19], v[20:23]
	s_nop 2
	ds_read_b128 v[20:23], v70 offset:8640
	s_waitcnt lgkmcnt(0)
	v_mfma_f32_16x16x32_bf16 v[12:15], v[20:23], v[12:15], v[16:19]
	s_nop 2
	v_lshl_add_u64 v[16:17], v[64:65], 0, s[0:1]
	v_mov_b32_e32 v20, v207
	global_load_dwordx2 v[84:85], v[16:17], off
	v_add_u32_e32 v16, s90, v77
	v_and_b32_e32 v91, 63, v20
	v_or_b32_e32 v16, v91, v16
	v_ashrrev_i32_e32 v17, 31, v16
	v_lshl_add_u64 v[16:17], v[16:17], 3, s[60:61]
	global_load_dwordx2 v[82:83], v[16:17], off
	v_add_u32_e32 v16, s91, v76
	v_ashrrev_i32_e32 v17, 31, v16
	v_and_b32_e32 v92, 15, v20
	v_lshlrev_b64 v[16:17], 12, v[16:17]
	v_lshl_add_u64 v[18:19], s[62:63], 0, v[16:17]
	v_lshlrev_b32_e32 v21, 4, v92
	v_and_b32_e32 v128, 48, v20
	v_cmp_gt_u32_e64 s[42:43], 32, v91
	v_lshl_add_u64 v[18:19], v[18:19], 0, v[128:129]
	v_lshlrev_b32_e32 v128, 1, v21
	s_and_saveexec_b64 s[0:1], s[42:43]
	s_cbranch_execz .LBB0_1789
	v_lshl_add_u64 v[22:23], v[18:19], 0, v[128:129]
	global_load_dwordx4 v[40:43], v[22:23], off

.LBB0_1811:
	s_or_b64 exec, exec, s[0:1]
	s_waitcnt vmcnt(0) lgkmcnt(0)
	v_mov_b32_e32 v158, 0x5040100
	v_mov_b32_e32 v159, 0x7060302
	v_perm_b32 v32, v142, v140, v158
	v_perm_b32 v33, v142, v140, v159
	v_perm_b32 v34, v143, v141, v158
	v_perm_b32 v35, v143, v141, v159
	v_perm_b32 v28, v146, v144, v158
	v_perm_b32 v29, v146, v144, v159
	v_perm_b32 v30, v147, v145, v158
	v_perm_b32 v31, v147, v145, v159
	v_perm_b32 v24, v150, v148, v158
	v_perm_b32 v25, v150, v148, v159
	v_perm_b32 v26, v151, v149, v158
	v_perm_b32 v27, v151, v149, v159
	v_perm_b32 v20, v154, v152, v158
	v_perm_b32 v21, v154, v152, v159
	v_perm_b32 v22, v155, v153, v158
	v_perm_b32 v23, v155, v153, v159
	v_mfma_f32_16x16x32_bf16 v[94:97], v[16:19], v[40:43], 0
	v_mul_u32_u24_e32 v86, 0x210, v93
	v_lshlrev_b32_e32 v87, 2, v92
	v_lshlrev_b32_e32 v86, 2, v86
	v_mfma_f32_16x16x32_bf16 v[98:101], v[16:19], v[36:39], 0
	v_add3_u32 v88, v81, v87, v86
	v_add_u32_e32 v89, 0x400, v88
	v_mul_u32_u24_e32 v103, 0x110, v92
	s_nop 4
	ds_write2_b32 v88, v94, v98 offset1:16
	ds_write2_b32 v88, v95, v99 offset0:132 offset1:148
	ds_write2_b32 v89, v96, v100 offset0:8 offset1:24
	ds_write2_b32 v89, v97, v101 offset0:140 offset1:156
	v_mfma_f32_16x16x32_bf16 v[92:95], v[16:19], v[48:51], 0
	v_lshl_add_u32 v87, v91, 2, v81
	v_add3_u32 v81, v81, v128, v103
	v_pk_add_f32 v[0:1], v[0:1], 0 op_sel_hi:[1,0]
	v_mfma_f32_16x16x32_bf16 v[96:99], v[16:19], v[44:47], 0
	s_nop 7
	ds_write2_b32 v88, v92, v96 offset0:32 offset1:48
	ds_write2_b32 v88, v93, v97 offset0:164 offset1:180
	ds_write2_b32 v89, v94, v98 offset0:40 offset1:56
	ds_write2_b32 v89, v95, v99 offset0:172 offset1:188
	v_mfma_f32_16x16x32_bf16 v[92:95], v[16:19], v[56:59], 0
	v_readlane_b32 s68, v251, 41
	v_readlane_b32 s76, v251, 49
	v_readlane_b32 s77, v251, 50
	v_mfma_f32_16x16x32_bf16 v[96:99], v[16:19], v[52:55], 0
	s_nop 7
	ds_write2_b32 v88, v92, v96 offset0:64 offset1:80
	ds_write2_b32 v88, v93, v97 offset0:196 offset1:212
	ds_write2_b32 v89, v94, v98 offset0:72 offset1:88
	ds_write2_b32 v89, v95, v99 offset0:204 offset1:220
	v_mfma_f32_16x16x32_bf16 v[92:95], v[16:19], v[64:67], 0
	s_mov_b32 s10, 0x3f200000
	v_readlane_b32 s69, v251, 42
	v_readlane_b32 s70, v251, 43
	v_mfma_f32_16x16x32_bf16 v[16:19], v[16:19], v[60:63], 0
	s_nop 7
	ds_write2_b32 v88, v92, v16 offset0:96 offset1:112
	ds_write2_b32 v88, v93, v17 offset0:228 offset1:244
	ds_write2_b32 v89, v94, v18 offset0:104 offset1:120
	ds_write2_b32 v89, v95, v19 offset0:236 offset1:252
	v_lshlrev_b32_e32 v16, 1, v91
	v_add_u32_e32 v91, 0xf0, v87
	s_waitcnt vmcnt(0) lgkmcnt(0)
	v_sub_u32_e32 v86, v87, v16
	ds_read2st64_b32 v[16:17], v91 offset0:30 offset1:31
	v_add_u32_e32 v140, 0xe0, v87
	ds_read2st64_b32 v[142:143], v140 offset0:28 offset1:29
	v_add_u32_e32 v141, 0xd0, v87
	ds_read2st64_b32 v[144:145], v141 offset0:26 offset1:27
	v_add_u32_e32 v146, 0xc0, v87
	ds_read2st64_b32 v[148:149], v146 offset0:24 offset1:25
	v_add_u32_e32 v147, 0xb0, v87
	ds_read2st64_b32 v[150:151], v147 offset0:22 offset1:23
	v_add_u32_e32 v152, 0xa0, v87
	ds_read2st64_b32 v[154:155], v152 offset0:20 offset1:21
	v_add_u32_e32 v153, 0x90, v87
	ds_read2st64_b32 v[156:157], v153 offset0:18 offset1:19
	v_add_u32_e32 v158, 0x80, v87
	ds_read2st64_b32 v[160:161], v158 offset0:16 offset1:17
	v_add_u32_e32 v159, 0x70, v87
	ds_read2st64_b32 v[162:163], v159 offset0:14 offset1:15
	v_add_u32_e32 v164, 0x60, v87
	ds_read2st64_b32 v[166:167], v164 offset0:12 offset1:13
	v_add_u32_e32 v165, 0x50, v87
	ds_read2st64_b32 v[168:169], v165 offset0:10 offset1:11
	v_add_u32_e32 v170, 64, v87
	ds_read2st64_b32 v[172:173], v170 offset0:8 offset1:9
	v_add_u32_e32 v171, 48, v87
	ds_read2st64_b32 v[174:175], v171 offset0:6 offset1:7
	v_add_u32_e32 v176, 32, v87
	ds_read2st64_b32 v[178:179], v176 offset0:4 offset1:5
	ds_read2_b32 v[180:181], v87 offset0:132 offset1:196
	ds_read2st64_b32 v[182:183], v87 offset1:1
	v_mov_b32_e32 v186, v84
	v_mov_b32_e32 v187, v85
	v_mfma_f32_16x16x32_bf16 v[108:111], v[72:75], v[36:39], 0
	v_readlane_b32 s71, v251, 44
	s_waitcnt lgkmcnt(0)
	v_fma_f32 v184, -v83, v187, v16
	v_fma_f32 v185, v83, v186, v17
	v_fma_f32 v188, v82, v186, v184
	v_fma_f32 v189, v82, v187, v185
	v_cvt_pk_bf16_f32 v190, v188, v189
	v_and_b32_e32 v191, 63, v207
	v_lshl_add_u32 v191, v191, 1, v86
	ds_write_b32 v191, v190 offset:12528
	v_add_u32_e32 v84, 0xe0, v87
	v_readlane_b32 s72, v251, 45
	v_readlane_b32 s73, v251, 46
	v_fma_f32 v184, -v83, v189, v142
	v_fma_f32 v185, v83, v188, v143
	v_fma_f32 v186, v82, v188, v184
	v_fma_f32 v187, v82, v189, v185
	v_cvt_pk_bf16_f32 v190, v186, v187
	ds_write_b32 v191, v190 offset:12256
	v_add_u32_e32 v85, 0xd0, v87
	v_readlane_b32 s74, v251, 47
	v_readlane_b32 s75, v251, 48
	v_fma_f32 v184, -v83, v187, v144
	v_fma_f32 v185, v83, v186, v145
	v_fma_f32 v188, v82, v186, v184
	v_fma_f32 v189, v82, v187, v185
	v_cvt_pk_bf16_f32 v190, v188, v189
	ds_write_b32 v191, v190 offset:11984
	v_add_u32_e32 v92, 0xc0, v87
	v_readlane_b32 s78, v251, 51
	v_readlane_b32 s79, v251, 52
	v_fma_f32 v184, -v83, v189, v148
	v_fma_f32 v185, v83, v188, v149
	v_fma_f32 v186, v82, v188, v184
	v_fma_f32 v187, v82, v189, v185
	v_cvt_pk_bf16_f32 v190, v186, v187
	ds_write_b32 v191, v190 offset:11712
	v_add_u32_e32 v93, 0xb0, v87
	v_readlane_b32 s80, v251, 53
	v_readlane_b32 s81, v251, 54
	v_fma_f32 v184, -v83, v187, v150
	v_fma_f32 v185, v83, v186, v151
	v_fma_f32 v188, v82, v186, v184
	v_fma_f32 v189, v82, v187, v185
	v_cvt_pk_bf16_f32 v190, v188, v189
	ds_write_b32 v191, v190 offset:11440
	v_add_u32_e32 v94, 0xa0, v87
	v_readlane_b32 s82, v251, 55
	v_readlane_b32 s83, v251, 56
	v_fma_f32 v184, -v83, v189, v154
	v_fma_f32 v185, v83, v188, v155
	v_fma_f32 v186, v82, v188, v184
	v_fma_f32 v187, v82, v189, v185
	v_cvt_pk_bf16_f32 v190, v186, v187
	ds_write_b32 v191, v190 offset:11168
	v_add_u32_e32 v95, 0x90, v87
	v_fma_f32 v184, -v83, v187, v156
	v_fma_f32 v185, v83, v186, v157
	v_fma_f32 v188, v82, v186, v184
	v_fma_f32 v189, v82, v187, v185
	v_cvt_pk_bf16_f32 v190, v188, v189
	ds_write_b32 v191, v190 offset:10896
	v_add_u32_e32 v96, 0x80, v87
	v_fma_f32 v184, -v83, v189, v160
	v_fma_f32 v185, v83, v188, v161
	v_fma_f32 v186, v82, v188, v184
	v_fma_f32 v187, v82, v189, v185
	v_cvt_pk_bf16_f32 v190, v186, v187
	ds_write_b32 v191, v190 offset:10624
	v_add_u32_e32 v97, 0x70, v87
	v_fma_f32 v184, -v83, v187, v162
	v_fma_f32 v185, v83, v186, v163
	v_fma_f32 v188, v82, v186, v184
	v_fma_f32 v189, v82, v187, v185
	v_cvt_pk_bf16_f32 v190, v188, v189
	ds_write_b32 v191, v190 offset:10352
	v_add_u32_e32 v98, 0x60, v87
	v_fma_f32 v184, -v83, v189, v166
	v_fma_f32 v185, v83, v188, v167
	v_fma_f32 v186, v82, v188, v184
	v_fma_f32 v187, v82, v189, v185
	v_cvt_pk_bf16_f32 v190, v186, v187
	ds_write_b32 v191, v190 offset:10080
	v_add_u32_e32 v99, 0x50, v87
	v_fma_f32 v184, -v83, v187, v168
	v_fma_f32 v185, v83, v186, v169
	v_fma_f32 v188, v82, v186, v184
	v_fma_f32 v189, v82, v187, v185
	v_cvt_pk_bf16_f32 v190, v188, v189
	ds_write_b32 v191, v190 offset:9808
	v_add_u32_e32 v100, 64, v87
	v_fma_f32 v184, -v83, v189, v172
	v_fma_f32 v185, v83, v188, v173
	v_fma_f32 v186, v82, v188, v184
	v_fma_f32 v187, v82, v189, v185
	v_cvt_pk_bf16_f32 v190, v186, v187
	ds_write_b32 v191, v190 offset:9536
	v_add_u32_e32 v101, 48, v87
	v_fma_f32 v184, -v83, v187, v174
	v_fma_f32 v185, v83, v186, v175
	v_fma_f32 v188, v82, v186, v184
	v_fma_f32 v189, v82, v187, v185
	v_cvt_pk_bf16_f32 v190, v188, v189
	ds_write_b32 v191, v190 offset:9264
	v_add_u32_e32 v102, 32, v87
	v_fma_f32 v184, -v83, v189, v178
	v_fma_f32 v185, v83, v188, v179
	v_fma_f32 v186, v82, v188, v184
	v_fma_f32 v187, v82, v189, v185
	v_cvt_pk_bf16_f32 v190, v186, v187
	ds_write_b32 v191, v190 offset:8992
	v_fma_f32 v184, -v83, v187, v180
	v_fma_f32 v185, v83, v186, v181
	v_fma_f32 v188, v82, v186, v184
	v_fma_f32 v189, v82, v187, v185
	v_cvt_pk_bf16_f32 v190, v188, v189
	ds_write_b32 v191, v190 offset:8720
	v_fma_f32 v184, -v83, v189, v182
	v_fma_f32 v185, v83, v188, v183
	v_fma_f32 v186, v82, v188, v184
	v_fma_f32 v187, v82, v189, v185
	v_mov_b32_e32 v112, v186
	v_mov_b32_e32 v113, v187
	v_cvt_pk_bf16_f32 v190, v186, v187
	ds_write_b32 v191, v190 offset:8448
	s_waitcnt vmcnt(0) lgkmcnt(0)
	ds_read_b128 v[16:19], v81 offset:8448
	ds_read_b128 v[104:107], v81 offset:8512
	s_waitcnt lgkmcnt(1)
	v_mfma_f32_16x16x32_bf16 v[16:19], v[16:19], v[32:35], 0
	s_waitcnt lgkmcnt(0)
	v_mfma_f32_16x16x32_bf16 v[16:19], v[104:107], v[28:31], v[16:19]
	ds_read_b128 v[104:107], v81 offset:8576
	s_waitcnt lgkmcnt(0)
	v_mfma_f32_16x16x32_bf16 v[16:19], v[104:107], v[24:27], v[16:19]
	ds_read_b128 v[104:107], v81 offset:8640
	s_waitcnt lgkmcnt(0)
	v_mfma_f32_16x16x32_bf16 v[16:19], v[104:107], v[20:23], v[16:19]
	v_mfma_f32_16x16x32_bf16 v[104:107], v[72:75], v[40:43], 0
	s_nop 7
	ds_write2_b32 v88, v104, v108 offset1:16
	ds_write2_b32 v88, v105, v109 offset0:132 offset1:148
	ds_write2_b32 v89, v106, v110 offset0:8 offset1:24
	ds_write2_b32 v89, v107, v111 offset0:140 offset1:156
	v_mfma_f32_16x16x32_bf16 v[104:107], v[72:75], v[48:51], 0
	v_mfma_f32_16x16x32_bf16 v[108:111], v[72:75], v[44:47], 0
	s_nop 7
	ds_write2_b32 v88, v104, v108 offset0:32 offset1:48
	ds_write2_b32 v88, v105, v109 offset0:164 offset1:180
	ds_write2_b32 v89, v106, v110 offset0:40 offset1:56
	ds_write2_b32 v89, v107, v111 offset0:172 offset1:188
	v_mfma_f32_16x16x32_bf16 v[104:107], v[72:75], v[56:59], 0
	v_mfma_f32_16x16x32_bf16 v[108:111], v[72:75], v[52:55], 0
	s_nop 7
	ds_write2_b32 v88, v104, v108 offset0:64 offset1:80
	ds_write2_b32 v88, v105, v109 offset0:196 offset1:212
	ds_write2_b32 v89, v106, v110 offset0:72 offset1:88
	ds_write2_b32 v89, v107, v111 offset0:204 offset1:220
	v_mfma_f32_16x16x32_bf16 v[104:107], v[72:75], v[64:67], 0
	v_mfma_f32_16x16x32_bf16 v[72:75], v[72:75], v[60:63], 0
	s_nop 7
	ds_write2_b32 v88, v104, v72 offset0:96 offset1:112
	ds_write2_b32 v88, v105, v73 offset0:228 offset1:244
	ds_write2_b32 v89, v106, v74 offset0:104 offset1:120
	ds_write2_b32 v89, v107, v75 offset0:236 offset1:252
	s_waitcnt vmcnt(0) lgkmcnt(0)
	ds_read2st64_b32 v[72:73], v91 offset0:30 offset1:31
	ds_read2st64_b32 v[140:141], v84 offset0:28 offset1:29
	ds_read2st64_b32 v[142:143], v85 offset0:26 offset1:27
	ds_read2st64_b32 v[144:145], v92 offset0:24 offset1:25
	ds_read2st64_b32 v[146:147], v93 offset0:22 offset1:23
	ds_read2st64_b32 v[148:149], v94 offset0:20 offset1:21
	ds_read2st64_b32 v[150:151], v95 offset0:18 offset1:19
	ds_read2st64_b32 v[152:153], v96 offset0:16 offset1:17
	ds_read2st64_b32 v[154:155], v97 offset0:14 offset1:15
	ds_read2st64_b32 v[156:157], v98 offset0:12 offset1:13
	ds_read2st64_b32 v[158:159], v99 offset0:10 offset1:11
	ds_read2st64_b32 v[160:161], v100 offset0:8 offset1:9
	ds_read2st64_b32 v[162:163], v101 offset0:6 offset1:7
	ds_read2st64_b32 v[164:165], v102 offset0:4 offset1:5
	ds_read2_b32 v[166:167], v87 offset0:132 offset1:196
	ds_read2st64_b32 v[168:169], v87 offset1:1
	v_mov_b32_e32 v186, v112
	v_mov_b32_e32 v187, v113
	v_mfma_f32_16x16x32_bf16 v[108:111], v[76:79], v[36:39], 0
	s_waitcnt lgkmcnt(0)
	v_fma_f32 v184, -v83, v187, v72
	v_fma_f32 v185, v83, v186, v73
	v_fma_f32 v188, v82, v186, v184
	v_fma_f32 v189, v82, v187, v185
	v_cvt_pk_bf16_f32 v190, v188, v189
	v_and_b32_e32 v191, 63, v207
	v_lshl_add_u32 v191, v191, 1, v86
	ds_write_b32 v191, v190 offset:12528
	v_mfma_f32_16x16x32_bf16 v[36:39], v[68:71], v[36:39], 0
	v_fma_f32 v184, -v83, v189, v140
	v_fma_f32 v185, v83, v188, v141
	v_fma_f32 v186, v82, v188, v184
	v_fma_f32 v187, v82, v189, v185
	v_cvt_pk_bf16_f32 v190, v186, v187
	ds_write_b32 v191, v190 offset:12256
	v_fma_f32 v184, -v83, v187, v142
	v_fma_f32 v185, v83, v186, v143
	v_fma_f32 v188, v82, v186, v184
	v_fma_f32 v189, v82, v187, v185
	v_cvt_pk_bf16_f32 v190, v188, v189
	ds_write_b32 v191, v190 offset:11984
	v_fma_f32 v184, -v83, v189, v144
	v_fma_f32 v185, v83, v188, v145
	v_fma_f32 v186, v82, v188, v184
	v_fma_f32 v187, v82, v189, v185
	v_cvt_pk_bf16_f32 v190, v186, v187
	ds_write_b32 v191, v190 offset:11712
	v_fma_f32 v184, -v83, v187, v146
	v_fma_f32 v185, v83, v186, v147
	v_fma_f32 v188, v82, v186, v184
	v_fma_f32 v189, v82, v187, v185
	v_cvt_pk_bf16_f32 v190, v188, v189
	ds_write_b32 v191, v190 offset:11440
	v_fma_f32 v184, -v83, v189, v148
	v_fma_f32 v185, v83, v188, v149
	v_fma_f32 v186, v82, v188, v184
	v_fma_f32 v187, v82, v189, v185
	v_cvt_pk_bf16_f32 v190, v186, v187
	ds_write_b32 v191, v190 offset:11168
	v_fma_f32 v184, -v83, v187, v150
	v_fma_f32 v185, v83, v186, v151
	v_fma_f32 v188, v82, v186, v184
	v_fma_f32 v189, v82, v187, v185
	v_cvt_pk_bf16_f32 v190, v188, v189
	ds_write_b32 v191, v190 offset:10896
	v_fma_f32 v184, -v83, v189, v152
	v_fma_f32 v185, v83, v188, v153
	v_fma_f32 v186, v82, v188, v184
	v_fma_f32 v187, v82, v189, v185
	v_cvt_pk_bf16_f32 v190, v186, v187
	ds_write_b32 v191, v190 offset:10624
	v_fma_f32 v184, -v83, v187, v154
	v_fma_f32 v185, v83, v186, v155
	v_fma_f32 v188, v82, v186, v184
	v_fma_f32 v189, v82, v187, v185
	v_cvt_pk_bf16_f32 v190, v188, v189
	ds_write_b32 v191, v190 offset:10352
	v_fma_f32 v184, -v83, v189, v156
	v_fma_f32 v185, v83, v188, v157
	v_fma_f32 v186, v82, v188, v184
	v_fma_f32 v187, v82, v189, v185
	v_cvt_pk_bf16_f32 v190, v186, v187
	ds_write_b32 v191, v190 offset:10080
	v_fma_f32 v184, -v83, v187, v158
	v_fma_f32 v185, v83, v186, v159
	v_fma_f32 v188, v82, v186, v184
	v_fma_f32 v189, v82, v187, v185
	v_cvt_pk_bf16_f32 v190, v188, v189
	ds_write_b32 v191, v190 offset:9808
	v_fma_f32 v184, -v83, v189, v160
	v_fma_f32 v185, v83, v188, v161
	v_fma_f32 v186, v82, v188, v184
	v_fma_f32 v187, v82, v189, v185
	v_cvt_pk_bf16_f32 v190, v186, v187
	ds_write_b32 v191, v190 offset:9536
	v_fma_f32 v184, -v83, v187, v162
	v_fma_f32 v185, v83, v186, v163
	v_fma_f32 v188, v82, v186, v184
	v_fma_f32 v189, v82, v187, v185
	v_cvt_pk_bf16_f32 v190, v188, v189
	ds_write_b32 v191, v190 offset:9264
	v_fma_f32 v184, -v83, v189, v164
	v_fma_f32 v185, v83, v188, v165
	v_fma_f32 v186, v82, v188, v184
	v_fma_f32 v187, v82, v189, v185
	v_cvt_pk_bf16_f32 v190, v186, v187
	ds_write_b32 v191, v190 offset:8992
	v_fma_f32 v184, -v83, v187, v166
	v_fma_f32 v185, v83, v186, v167
	v_fma_f32 v188, v82, v186, v184
	v_fma_f32 v189, v82, v187, v185
	v_cvt_pk_bf16_f32 v190, v188, v189
	ds_write_b32 v191, v190 offset:8720
	v_fma_f32 v184, -v83, v189, v168
	v_fma_f32 v185, v83, v188, v169
	v_fma_f32 v186, v82, v188, v184
	v_fma_f32 v187, v82, v189, v185
	v_mov_b32_e32 v103, v186
	v_mov_b32_e32 v112, v187
	v_cvt_pk_bf16_f32 v190, v186, v187
	ds_write_b32 v191, v190 offset:8448
	s_waitcnt vmcnt(0) lgkmcnt(0)
	ds_read_b128 v[72:75], v81 offset:8448
	ds_read_b128 v[104:107], v81 offset:8512
	s_waitcnt lgkmcnt(1)
	v_mfma_f32_16x16x32_bf16 v[72:75], v[72:75], v[32:35], 0
	s_waitcnt lgkmcnt(0)
	v_mfma_f32_16x16x32_bf16 v[72:75], v[104:107], v[28:31], v[72:75]
	ds_read_b128 v[104:107], v81 offset:8576
	s_waitcnt lgkmcnt(0)
	v_mfma_f32_16x16x32_bf16 v[72:75], v[104:107], v[24:27], v[72:75]
	ds_read_b128 v[104:107], v81 offset:8640
	s_waitcnt lgkmcnt(0)
	v_mfma_f32_16x16x32_bf16 v[72:75], v[104:107], v[20:23], v[72:75]
	v_mfma_f32_16x16x32_bf16 v[104:107], v[76:79], v[40:43], 0
	s_nop 7
	ds_write2_b32 v88, v104, v108 offset1:16
	ds_write2_b32 v88, v105, v109 offset0:132 offset1:148
	ds_write2_b32 v89, v106, v110 offset0:8 offset1:24
	ds_write2_b32 v89, v107, v111 offset0:140 offset1:156
	v_mfma_f32_16x16x32_bf16 v[104:107], v[76:79], v[48:51], 0
	v_mfma_f32_16x16x32_bf16 v[108:111], v[76:79], v[44:47], 0
	s_nop 7
	ds_write2_b32 v88, v104, v108 offset0:32 offset1:48
	ds_write2_b32 v88, v105, v109 offset0:164 offset1:180
	ds_write2_b32 v89, v106, v110 offset0:40 offset1:56
	ds_write2_b32 v89, v107, v111 offset0:172 offset1:188
	v_mfma_f32_16x16x32_bf16 v[104:107], v[76:79], v[56:59], 0
	v_mfma_f32_16x16x32_bf16 v[108:111], v[76:79], v[52:55], 0
	s_nop 7
	ds_write2_b32 v88, v104, v108 offset0:64 offset1:80
	ds_write2_b32 v88, v105, v109 offset0:196 offset1:212
	ds_write2_b32 v89, v106, v110 offset0:72 offset1:88
	ds_write2_b32 v89, v107, v111 offset0:204 offset1:220
	v_mfma_f32_16x16x32_bf16 v[104:107], v[76:79], v[64:67], 0
	v_mfma_f32_16x16x32_bf16 v[76:79], v[76:79], v[60:63], 0
	s_nop 7
	ds_write2_b32 v88, v104, v76 offset0:96 offset1:112
	ds_write2_b32 v88, v105, v77 offset0:228 offset1:244
	ds_write2_b32 v89, v106, v78 offset0:104 offset1:120
	ds_write2_b32 v89, v107, v79 offset0:236 offset1:252
	s_waitcnt vmcnt(0) lgkmcnt(0)
	ds_read2st64_b32 v[76:77], v91 offset0:30 offset1:31
	ds_read2st64_b32 v[140:141], v84 offset0:28 offset1:29
	ds_read2st64_b32 v[142:143], v85 offset0:26 offset1:27
	ds_read2st64_b32 v[144:145], v92 offset0:24 offset1:25
	ds_read2st64_b32 v[146:147], v93 offset0:22 offset1:23
	ds_read2st64_b32 v[148:149], v94 offset0:20 offset1:21
	ds_read2st64_b32 v[150:151], v95 offset0:18 offset1:19
	ds_read2st64_b32 v[152:153], v96 offset0:16 offset1:17
	ds_read2st64_b32 v[154:155], v97 offset0:14 offset1:15
	ds_read2st64_b32 v[156:157], v98 offset0:12 offset1:13
	ds_read2st64_b32 v[158:159], v99 offset0:10 offset1:11
	ds_read2st64_b32 v[160:161], v100 offset0:8 offset1:9
	ds_read2st64_b32 v[162:163], v101 offset0:6 offset1:7
	ds_read2st64_b32 v[164:165], v102 offset0:4 offset1:5
	ds_read2_b32 v[166:167], v87 offset0:132 offset1:196
	ds_read2st64_b32 v[168:169], v87 offset1:1
	v_mov_b32_e32 v186, v103
	v_mov_b32_e32 v187, v112
	v_mfma_f32_16x16x32_bf16 v[40:43], v[68:71], v[40:43], 0
	s_waitcnt lgkmcnt(0)
	v_fma_f32 v184, -v83, v187, v76
	v_fma_f32 v185, v83, v186, v77
	v_fma_f32 v188, v82, v186, v184
	v_fma_f32 v189, v82, v187, v185
	v_cvt_pk_bf16_f32 v190, v188, v189
	v_and_b32_e32 v191, 63, v207
	v_lshl_add_u32 v191, v191, 1, v86
	ds_write_b32 v191, v190 offset:12528
	v_fma_f32 v184, -v83, v189, v140
	v_fma_f32 v185, v83, v188, v141
	v_fma_f32 v186, v82, v188, v184
	v_fma_f32 v187, v82, v189, v185
	v_cvt_pk_bf16_f32 v190, v186, v187
	ds_write_b32 v191, v190 offset:12256
	v_fma_f32 v184, -v83, v187, v142
	v_fma_f32 v185, v83, v186, v143
	v_fma_f32 v188, v82, v186, v184
	v_fma_f32 v189, v82, v187, v185
	v_cvt_pk_bf16_f32 v190, v188, v189
	ds_write_b32 v191, v190 offset:11984
	v_fma_f32 v184, -v83, v189, v144
	v_fma_f32 v185, v83, v188, v145
	v_fma_f32 v186, v82, v188, v184
	v_fma_f32 v187, v82, v189, v185
	v_cvt_pk_bf16_f32 v190, v186, v187
	ds_write_b32 v191, v190 offset:11712
	v_fma_f32 v184, -v83, v187, v146
	v_fma_f32 v185, v83, v186, v147
	v_fma_f32 v188, v82, v186, v184
	v_fma_f32 v189, v82, v187, v185
	v_cvt_pk_bf16_f32 v190, v188, v189
	ds_write_b32 v191, v190 offset:11440
	v_fma_f32 v184, -v83, v189, v148
	v_fma_f32 v185, v83, v188, v149
	v_fma_f32 v186, v82, v188, v184
	v_fma_f32 v187, v82, v189, v185
	v_cvt_pk_bf16_f32 v190, v186, v187
	ds_write_b32 v191, v190 offset:11168
	v_fma_f32 v184, -v83, v187, v150
	v_fma_f32 v185, v83, v186, v151
	v_fma_f32 v188, v82, v186, v184
	v_fma_f32 v189, v82, v187, v185
	v_cvt_pk_bf16_f32 v190, v188, v189
	ds_write_b32 v191, v190 offset:10896
	v_fma_f32 v184, -v83, v189, v152
	v_fma_f32 v185, v83, v188, v153
	v_fma_f32 v186, v82, v188, v184
	v_fma_f32 v187, v82, v189, v185
	v_cvt_pk_bf16_f32 v190, v186, v187
	ds_write_b32 v191, v190 offset:10624
	v_fma_f32 v184, -v83, v187, v154
	v_fma_f32 v185, v83, v186, v155
	v_fma_f32 v188, v82, v186, v184
	v_fma_f32 v189, v82, v187, v185
	v_cvt_pk_bf16_f32 v190, v188, v189
	ds_write_b32 v191, v190 offset:10352
	v_fma_f32 v184, -v83, v189, v156
	v_fma_f32 v185, v83, v188, v157
	v_fma_f32 v186, v82, v188, v184
	v_fma_f32 v187, v82, v189, v185
	v_cvt_pk_bf16_f32 v190, v186, v187
	ds_write_b32 v191, v190 offset:10080
	v_fma_f32 v184, -v83, v187, v158
	v_fma_f32 v185, v83, v186, v159
	v_fma_f32 v188, v82, v186, v184
	v_fma_f32 v189, v82, v187, v185
	v_cvt_pk_bf16_f32 v190, v188, v189
	ds_write_b32 v191, v190 offset:9808
	v_fma_f32 v184, -v83, v189, v160
	v_fma_f32 v185, v83, v188, v161
	v_fma_f32 v186, v82, v188, v184
	v_fma_f32 v187, v82, v189, v185
	v_cvt_pk_bf16_f32 v190, v186, v187
	ds_write_b32 v191, v190 offset:9536
	v_fma_f32 v184, -v83, v187, v162
	v_fma_f32 v185, v83, v186, v163
	v_fma_f32 v188, v82, v186, v184
	v_fma_f32 v189, v82, v187, v185
	v_cvt_pk_bf16_f32 v190, v188, v189
	ds_write_b32 v191, v190 offset:9264
	v_fma_f32 v184, -v83, v189, v164
	v_fma_f32 v185, v83, v188, v165
	v_fma_f32 v186, v82, v188, v184
	v_fma_f32 v187, v82, v189, v185
	v_cvt_pk_bf16_f32 v190, v186, v187
	ds_write_b32 v191, v190 offset:8992
	v_fma_f32 v184, -v83, v187, v166
	v_fma_f32 v185, v83, v186, v167
	v_fma_f32 v188, v82, v186, v184
	v_fma_f32 v189, v82, v187, v185
	v_cvt_pk_bf16_f32 v190, v188, v189
	ds_write_b32 v191, v190 offset:8720
	v_fma_f32 v184, -v83, v189, v168
	v_fma_f32 v185, v83, v188, v169
	v_fma_f32 v186, v82, v188, v184
	v_fma_f32 v187, v82, v189, v185
	v_mov_b32_e32 v103, v186
	v_mov_b32_e32 v108, v187
	v_cvt_pk_bf16_f32 v190, v186, v187
	ds_write_b32 v191, v190 offset:8448
	s_waitcnt vmcnt(0) lgkmcnt(0)
	ds_read_b128 v[76:79], v81 offset:8448
	ds_read_b128 v[104:107], v81 offset:8512
	s_waitcnt lgkmcnt(1)
	v_mfma_f32_16x16x32_bf16 v[76:79], v[76:79], v[32:35], 0
	s_waitcnt lgkmcnt(0)
	v_mfma_f32_16x16x32_bf16 v[76:79], v[104:107], v[28:31], v[76:79]
	ds_read_b128 v[104:107], v81 offset:8576
	s_waitcnt lgkmcnt(0)
	v_mfma_f32_16x16x32_bf16 v[76:79], v[104:107], v[24:27], v[76:79]
	ds_read_b128 v[104:107], v81 offset:8640
	ds_write2_b32 v88, v40, v36 offset1:16
	ds_write2_b32 v88, v41, v37 offset0:132 offset1:148
	ds_write2_b32 v89, v42, v38 offset0:8 offset1:24
	ds_write2_b32 v89, v43, v39 offset0:140 offset1:156
	v_mfma_f32_16x16x32_bf16 v[36:39], v[68:71], v[48:51], 0
	v_mfma_f32_16x16x32_bf16 v[40:43], v[68:71], v[44:47], 0
	s_nop 7
	ds_write2_b32 v88, v36, v40 offset0:32 offset1:48
	ds_write2_b32 v88, v37, v41 offset0:164 offset1:180
	ds_write2_b32 v89, v38, v42 offset0:40 offset1:56
	ds_write2_b32 v89, v39, v43 offset0:172 offset1:188
	v_mfma_f32_16x16x32_bf16 v[36:39], v[68:71], v[56:59], 0
	v_mfma_f32_16x16x32_bf16 v[40:43], v[68:71], v[52:55], 0
	s_nop 7
	ds_write2_b32 v88, v36, v40 offset0:64 offset1:80
	ds_write2_b32 v88, v37, v41 offset0:196 offset1:212
	ds_write2_b32 v89, v38, v42 offset0:72 offset1:88
	ds_write2_b32 v89, v39, v43 offset0:204 offset1:220
	v_mfma_f32_16x16x32_bf16 v[36:39], v[68:71], v[64:67], 0
	v_mfma_f32_16x16x32_bf16 v[40:43], v[68:71], v[60:63], 0
	s_nop 7
	ds_write2_b32 v88, v36, v40 offset0:96 offset1:112
	ds_write2_b32 v88, v37, v41 offset0:228 offset1:244
	ds_write2_b32 v89, v38, v42 offset0:104 offset1:120
	ds_write2_b32 v89, v39, v43 offset0:236 offset1:252
	s_waitcnt vmcnt(0) lgkmcnt(0)
	ds_read2st64_b32 v[36:37], v91 offset0:30 offset1:31
	ds_read2st64_b32 v[140:141], v84 offset0:28 offset1:29
	ds_read2st64_b32 v[142:143], v85 offset0:26 offset1:27
	ds_read2st64_b32 v[144:145], v92 offset0:24 offset1:25
	ds_read2st64_b32 v[146:147], v93 offset0:22 offset1:23
	ds_read2st64_b32 v[148:149], v94 offset0:20 offset1:21
	ds_read2st64_b32 v[150:151], v95 offset0:18 offset1:19
	ds_read2st64_b32 v[152:153], v96 offset0:16 offset1:17
	ds_read2st64_b32 v[154:155], v97 offset0:14 offset1:15
	ds_read2st64_b32 v[156:157], v98 offset0:12 offset1:13
	ds_read2st64_b32 v[158:159], v99 offset0:10 offset1:11
	ds_read2st64_b32 v[160:161], v100 offset0:8 offset1:9
	ds_read2st64_b32 v[162:163], v101 offset0:6 offset1:7
	ds_read2st64_b32 v[164:165], v102 offset0:4 offset1:5
	ds_read2_b32 v[166:167], v87 offset0:132 offset1:196
	ds_read2st64_b32 v[168:169], v87 offset1:1
	v_mov_b32_e32 v186, v103
	v_mov_b32_e32 v187, v108
	s_waitcnt lgkmcnt(0)
	v_mfma_f32_16x16x32_bf16 v[76:79], v[104:107], v[20:23], v[76:79]
	v_fma_f32 v184, -v83, v187, v36
	v_fma_f32 v185, v83, v186, v37
	v_fma_f32 v188, v82, v186, v184
	v_fma_f32 v189, v82, v187, v185
	v_cvt_pk_bf16_f32 v190, v188, v189
	v_and_b32_e32 v191, 63, v207
	v_lshl_add_u32 v191, v191, 1, v86
	ds_write_b32 v191, v190 offset:12528
	v_fma_f32 v184, -v83, v189, v140
	v_fma_f32 v185, v83, v188, v141
	v_fma_f32 v186, v82, v188, v184
	v_fma_f32 v187, v82, v189, v185
	v_cvt_pk_bf16_f32 v190, v186, v187
	ds_write_b32 v191, v190 offset:12256
	v_fma_f32 v184, -v83, v187, v142
	v_fma_f32 v185, v83, v186, v143
	v_fma_f32 v188, v82, v186, v184
	v_fma_f32 v189, v82, v187, v185
	v_cvt_pk_bf16_f32 v190, v188, v189
	ds_write_b32 v191, v190 offset:11984
	v_fma_f32 v184, -v83, v189, v144
	v_fma_f32 v185, v83, v188, v145
	v_fma_f32 v186, v82, v188, v184
	v_fma_f32 v187, v82, v189, v185
	v_cvt_pk_bf16_f32 v190, v186, v187
	ds_write_b32 v191, v190 offset:11712
	v_fma_f32 v184, -v83, v187, v146
	v_fma_f32 v185, v83, v186, v147
	v_fma_f32 v188, v82, v186, v184
	v_fma_f32 v189, v82, v187, v185
	v_cvt_pk_bf16_f32 v190, v188, v189
	ds_write_b32 v191, v190 offset:11440
	v_fma_f32 v184, -v83, v189, v148
	v_fma_f32 v185, v83, v188, v149
	v_fma_f32 v186, v82, v188, v184
	v_fma_f32 v187, v82, v189, v185
	v_cvt_pk_bf16_f32 v190, v186, v187
	ds_write_b32 v191, v190 offset:11168
	v_fma_f32 v184, -v83, v187, v150
	v_fma_f32 v185, v83, v186, v151
	v_fma_f32 v188, v82, v186, v184
	v_fma_f32 v189, v82, v187, v185
	v_cvt_pk_bf16_f32 v190, v188, v189
	ds_write_b32 v191, v190 offset:10896
	v_fma_f32 v184, -v83, v189, v152
	v_fma_f32 v185, v83, v188, v153
	v_fma_f32 v186, v82, v188, v184
	v_fma_f32 v187, v82, v189, v185
	v_cvt_pk_bf16_f32 v190, v186, v187
	ds_write_b32 v191, v190 offset:10624
	v_fma_f32 v184, -v83, v187, v154
	v_fma_f32 v185, v83, v186, v155
	v_fma_f32 v188, v82, v186, v184
	v_fma_f32 v189, v82, v187, v185
	v_cvt_pk_bf16_f32 v190, v188, v189
	ds_write_b32 v191, v190 offset:10352
	v_fma_f32 v184, -v83, v189, v156
	v_fma_f32 v185, v83, v188, v157
	v_fma_f32 v186, v82, v188, v184
	v_fma_f32 v187, v82, v189, v185
	v_cvt_pk_bf16_f32 v190, v186, v187
	ds_write_b32 v191, v190 offset:10080
	v_fma_f32 v184, -v83, v187, v158
	v_fma_f32 v185, v83, v186, v159
	v_fma_f32 v188, v82, v186, v184
	v_fma_f32 v189, v82, v187, v185
	v_cvt_pk_bf16_f32 v190, v188, v189
	ds_write_b32 v191, v190 offset:9808
	v_fma_f32 v184, -v83, v189, v160
	v_fma_f32 v185, v83, v188, v161
	v_fma_f32 v186, v82, v188, v184
	v_fma_f32 v187, v82, v189, v185
	v_cvt_pk_bf16_f32 v190, v186, v187
	ds_write_b32 v191, v190 offset:9536
	v_fma_f32 v184, -v83, v187, v162
	v_fma_f32 v185, v83, v186, v163
	v_fma_f32 v188, v82, v186, v184
	v_fma_f32 v189, v82, v187, v185
	v_cvt_pk_bf16_f32 v190, v188, v189
	ds_write_b32 v191, v190 offset:9264
	v_fma_f32 v184, -v83, v189, v164
	v_fma_f32 v185, v83, v188, v165
	v_fma_f32 v186, v82, v188, v184
	v_fma_f32 v187, v82, v189, v185
	v_cvt_pk_bf16_f32 v190, v186, v187
	ds_write_b32 v191, v190 offset:8992
	v_fma_f32 v184, -v83, v187, v166
	v_fma_f32 v185, v83, v186, v167
	v_fma_f32 v188, v82, v186, v184
	v_fma_f32 v189, v82, v187, v185
	v_cvt_pk_bf16_f32 v190, v188, v189
	ds_write_b32 v191, v190 offset:8720
	v_fma_f32 v184, -v83, v189, v168
	v_fma_f32 v185, v83, v188, v169
	v_fma_f32 v186, v82, v188, v184
	v_fma_f32 v187, v82, v189, v185
	v_mov_b32_e32 v36, v186
	v_mov_b32_e32 v37, v187
	v_cvt_pk_bf16_f32 v190, v186, v187
	ds_write_b32 v191, v190 offset:8448
	s_waitcnt vmcnt(0) lgkmcnt(0)
	ds_read_b128 v[36:39], v81 offset:8448
	s_waitcnt lgkmcnt(0)
	v_mfma_f32_16x16x32_bf16 v[32:35], v[36:39], v[32:35], 0
	ds_read_b128 v[36:39], v81 offset:8512
	s_waitcnt lgkmcnt(0)
	v_mfma_f32_16x16x32_bf16 v[28:31], v[36:39], v[28:31], v[32:35]
	s_nop 4
	ds_read_b128 v[32:35], v81 offset:8576
	s_waitcnt lgkmcnt(0)
	v_mfma_f32_16x16x32_bf16 v[24:27], v[32:35], v[24:27], v[28:31]
	s_nop 2
	ds_read_b128 v[28:31], v81 offset:8640
	s_waitcnt lgkmcnt(0)
	v_mfma_f32_16x16x32_bf16 v[20:23], v[28:31], v[20:23], v[24:27]
	s_nop 7
	v_pk_add_f32 v[24:25], v[0:1], v[20:21]
	v_and_or_b32 v0, v90, 15, v80
	v_add_u32_e32 v20, s6, v0
	v_ashrrev_i32_e32 v21, 31, v20
	v_lshrrev_b32_e32 v1, 2, v90
	v_lshl_add_u64 v[20:21], v[20:21], 2, s[76:77]
	v_and_b32_e32 v1, 12, v1
	global_load_dword v28, v[20:21], off
	v_add_u32_e32 v20, s8, v1
	v_ashrrev_i32_e32 v21, 31, v20
	v_ashrrev_i32_e32 v1, 31, v0
	v_lshlrev_b64 v[26:27], 9, v[20:21]
	v_lshl_add_u64 v[26:27], v[26:27], 0, v[0:1]
	v_lshl_add_u64 v[30:31], v[26:27], 1, s[36:37]
	global_load_ushort v29, v[30:31], off
	global_load_ushort v141, v[30:31], off offset:1024
	global_load_ushort v142, v[30:31], off offset:2048
	global_load_ushort v143, v[30:31], off offset:3072
	s_mov_b64 s[0:1], 0x4000
	v_lshl_add_u64 v[156:157], v[30:31], 0, s[0:1]
	global_load_ushort v144, v[156:157], off
	global_load_ushort v145, v[156:157], off offset:1024
	global_load_ushort v146, v[156:157], off offset:2048
	global_load_ushort v147, v[156:157], off offset:3072
	s_mov_b64 s[0:1], 0x8000
	v_lshl_add_u64 v[158:159], v[30:31], 0, s[0:1]
	global_load_ushort v148, v[158:159], off
	global_load_ushort v149, v[158:159], off offset:1024
	global_load_ushort v150, v[158:159], off offset:2048
	global_load_ushort v151, v[158:159], off offset:3072
	s_mov_b64 s[0:1], 0xc000
	v_lshl_add_u64 v[160:161], v[30:31], 0, s[0:1]
	global_load_ushort v152, v[160:161], off
	global_load_ushort v153, v[160:161], off offset:1024
	global_load_ushort v154, v[160:161], off offset:2048
	global_load_ushort v155, v[160:161], off offset:3072
	s_waitcnt vmcnt(0) lgkmcnt(0)
	v_lshlrev_b32_e32 v29, 16, v29
	v_fma_f32 v24, v28, v29, v24
	v_mul_f32_e32 v29, 0x3d372713, v24
	v_mul_f32_e32 v29, v24, v29
	v_fma_f32 v29, v24, v29, v24
	v_mul_f32_e32 v29, 0x3f4c422a, v29
	v_cmp_nlt_f32_e64 s[0:1], |v29|, s10
	s_and_saveexec_b64 s[2:3], s[0:1]
	s_xor_b64 s[0:1], exec, s[2:3]
	s_cbranch_execz .LBB0_1813
	v_add_f32_e64 v30, |v29|, |v29|
	v_mul_f32_e32 v31, 0x3fb8aa3b, v30
	v_rndne_f32_e32 v32, v31
	s_mov_b32 s2, 0x3fb8aa3b
	v_sub_f32_e32 v33, v31, v32
	v_fma_f32 v31, v30, s2, -v31
	v_fmac_f32_e32 v31, 0x32a5705f, v30
	v_add_f32_e32 v31, v33, v31
	v_cvt_i32_f32_e32 v32, v32
	v_exp_f32_e32 v31, v31
	s_mov_b32 s2, 0xc2ce8ed0
	v_cmp_ngt_f32_e32 vcc, s2, v30
	s_mov_b32 s2, 0x42b17218
	v_ldexp_f32 v31, v31, v32
	v_cndmask_b32_e32 v31, 0, v31, vcc
	v_cmp_nlt_f32_e32 vcc, s2, v30
	s_nop 1
	v_cndmask_b32_e32 v30, v235, v31, vcc
	v_add_f32_e32 v30, 1.0, v30
	v_rcp_f32_e32 v30, v30
	s_nop 0
	v_fma_f32 v30, v30, -2.0, 1.0
